# v95 + nt on the attention phases' Q / gate loads (read once)
# speedup vs baseline: 1.0187x; 1.0086x over previous
; __device__ __forceinline__ void da_phase(LAS unsigned char* lds, const GAS f16* __restrict__ kv, const GAS f16* __restrict__ qg, GAS f16* __restrict__ mixed, int vcu, int G, ...
;     int tid_ = threadIdx.x; asm volatile("" : "+v"(tid_));
;     const int tid = tid_, lane = tid & 63, l31 = lane & 31, hi = lane >> 5; const int w = __builtin_amdgcn_readfirstlane(tid >> 6);
;     const int c = w >> 2, rg = (w + 2 * c) & 3;
;     const unsigned lds0 = (unsigned)(uintptr_t)lds;
;     const unsigned kdst = lds0 + w * 1024, vdst = lds0 + DA_VRING + w * 1024;
;     int kfo[4];
;     { const int kr = keyrow(l31);
; #pragma unroll
;       for (int d0 = 0; d0 < 4; ++d0) kfo[d0] = kr * 256 + (((8 * c + 2 * d0 + hi) ^ (kr & 15)) * 16); }
;     int vfo[4];
;     { const int q_ = (lane & 15) >> 2;
; #pragma unroll
;       for (int d0 = 0; d0 < 4; ++d0) vfo[d0] = DA_VRING + (32 * hi + q_) * 256 + ((d0 ^ q_) * 64) + ((lane >> 4) & 1) * 32 + (lane & 3) * 8; }
;     const int srow = 4 * w + (lane >> 4);
;     const size_t koff = (size_t)srow * KVW + K_DAK + (((lane & 15) ^ (srow & 15)) * 8);
;     const size_t voff = (size_t)srow * KVW + K_DAV + (((((lane & 15) >> 2) ^ (srow & 3)) * 4 + (lane & 3)) * 8);
;     const size_t qoff = S_DAQ * QG_SEC + bl512((size_t)(32 * rg + l31), c * 64 + 8 * hi);
;     h8 ones; { const f16 one = ((lane & 15) == ((lane >> 4) & 1)) ? (f16)1.0f : (f16)0.0f; ones = (h8){one, one, one, one, one, one, one, one}; }
;     h8 ba0, ba1; { const f16 z = (f16)0.0f, one = hi ? z : (f16)1.0f, k0 = hi ? z : (f16)(float)keyrow(l31), k1 = hi ? z : (f16)(float)(keyrow(l31) + 16);
;                    ba0 = (h8){one, one, k0, k0, z, z, z, z}; ba1 = (h8){one, one, k1, k1, z, z, z, z}; }
;     if (tid < 128) ((LAS float*)(lds + DA_SUBG))[tid] = subg[tid];
; __global__ void __launch_bounds__(NWAVES * 64, 2) hybrid_fwd(Args args) {
;     ...
;             const float sa = att::wave_sum(lq1[l * 64 + lane] * lk1[l * 64 + lane]), sb = att::wave_sum(lq2[l * 64 + lane] * lk2[l * 64 + lane]);
;             const float lam_init = 0.8f - 0.6f * __expf(-0.3f * (float)l);
;             const float lam = __expf(sa) - __expf(sb) + lam_init;
;             const float mgq = att::wave_max(fabsf(q_norm_g[l * 64 + lane])), mgk = att::wave_max(fabsf(k_norm_g[l * 64 + lane]));
;             const float mref = 8.0f * LOG2E * mgq * mgk * 1.001f - 10.0f;
.LBB0_488:
	v_add_f32_e32 v6, v2, v6
	v_cvt_f32_u32_e32 v2, s76
	v_add_f32_e32 v7, v7, v8
	v_readlane_b32 s4, v250, 2
	v_mul_f32_e32 v6, 0x3fb8aa3b, v6
	v_mul_f32_e32 v2, 0xbe99999a, v2
	v_mul_f32_e32 v2, 0x3fb8aa3b, v2
	v_mul_f32_e32 v7, 0x3fb8aa3b, v7
	v_readlane_b32 s5, v250, 3
	v_exp_f32_e32 v2, v2
	v_exp_f32_e32 v6, v6
	v_exp_f32_e32 v7, v7
	s_xor_b64 s[86:87], s[4:5], -1
	v_readlane_b32 s4, v250, 0
	s_waitcnt lgkmcnt(0)
	v_max_f32_e32 v8, v10, v10
	v_max_f32_e32 v5, v5, v5
	v_readlane_b32 s5, v250, 1
	s_add_u32 s33, s4, 0x6000000
	v_max_f32_e32 v8, v9, v8
	v_max_f32_e32 v4, v4, v5
	s_addc_u32 s26, s5, 0
	s_and_b64 vcc, exec, s[38:39]
	s_cbranch_vccnz .LBB0_531
	s_ashr_i32 s1, s0, 8
	s_ashr_i32 s4, s0, 6
	s_lshl_b32 s11, s1, 1
	s_add_i32 s11, s11, s4
	s_and_b32 s6, s11, 3
	s_lshl_b32 s5, s6, 13
	s_add_i32 s7, s5, 0
	s_add_i32 s7, s7, 0x1c000
	v_readlane_b32 s14, v250, 0
	v_readlane_b32 s15, v250, 1
	s_add_u32 s27, s14, 0x18000000
	s_addc_u32 s30, s15, 0
	v_bfe_u32 v14, v132, 5, 1
	s_lshl_b32 s36, s1, 6
	v_lshl_or_b32 v5, v14, 3, s36
	s_lshl_b32 s5, s4, 10
	s_lshl_b32 s22, s4, 2
	s_lshl_b32 s4, s11, 6
	v_ashrrev_i32_e32 v10, 3, v5
	s_and_b32 s80, s4, 0xc0
	v_ashrrev_i32_e32 v11, 31, v10
	v_lshl_add_u64 v[10:11], s[80:81], 0, v[10:11]
	s_add_i32 s31, s5, 0
	v_lshlrev_b64 v[10:11], 9, v[10:11]
	v_lshlrev_b32_e32 v5, 4, v132
	s_movk_i32 s4, 0x1f0
	s_lshl_b32 s21, s1, 3
	s_add_i32 s34, s31, 0xc000
	s_lshl_b32 s35, s6, 5
	v_and_or_b32 v10, v5, s4, v10
	v_readlane_b32 s4, v251, 8
	s_add_u32 s4, s8, s4
	s_addc_u32 s5, s9, 0
	v_readlane_b32 s14, v251, 49
	v_readlane_b32 s15, v251, 50
	s_add_u32 s4, s4, s14
	s_addc_u32 s5, s5, s15
	s_lshl_b32 s14, s10, 7
	s_ashr_i32 s15, s14, 31
	s_lshl_b64 s[14:15], s[14:15], 1
	v_readlane_b32 s18, v251, 9
	s_add_u32 s14, s14, s18
	s_addc_u32 s15, s15, 0
	s_and_b32 s15, s15, 0x7fffff
	s_and_b32 s14, s14, 0xffffff00
	v_readlane_b32 s18, v251, 10
	s_add_u32 s14, s14, s18
	v_readlane_b32 s18, v251, 11
	s_addc_u32 s15, s15, s18
	s_lshl_b64 s[14:15], s[14:15], 9
	s_add_u32 s14, s82, s14
	s_mov_b64 s[18:19], 0x4000000
	s_addc_u32 s15, s83, s15
	v_lshl_add_u64 v[10:11], v[10:11], 0, s[18:19]
	v_lshl_add_u64 v[12:13], s[14:15], 0, v[10:11]
	global_load_dwordx4 v[112:115], v[12:13], off offset:3072 nt
	global_load_dwordx4 v[108:111], v[12:13], off offset:2048 nt
	global_load_dwordx4 v[104:107], v[12:13], off offset:1024 nt
	global_load_dwordx4 v[100:103], v[12:13], off nt
	v_fmamk_f32 v2, v2, 0xbf19999a, v214
	v_sub_f32_e32 v5, v6, v7
	v_add_f32_e32 v15, v2, v5
	v_mul_f32_e32 v5, 0x4138aa3b, v8
	v_mul_f32_e32 v4, v5, v4
	v_fmamk_f32 v133, v4, 0x3f8020c5, v215
	v_lshlrev_b32_e32 v4, 3, v132
	v_lshrrev_b32_e32 v7, 1, v132
	v_and_b32_e32 v5, 32, v4
	v_and_b32_e32 v6, 3, v132
	v_and_b32_e32 v7, 12, v7
	v_or3_b32 v8, v6, v5, v7
	v_or_b32_e32 v6, v7, v6
	v_or_b32_e32 v5, s21, v14
	v_bitop3_b32 v7, s21, v6, v14 bitop3:0x36
	v_lshlrev_b32_e32 v175, 4, v7
	v_bitop3_b32 v7, v5, v6, 2 bitop3:0x36
	v_lshlrev_b32_e32 v176, 4, v7
	v_bitop3_b32 v7, v5, v6, 4 bitop3:0x36
	v_lshlrev_b32_e32 v177, 4, v7
	v_bitop3_b32 v5, v5, v6, 6 bitop3:0x36
	v_bfe_u32 v6, v132, 2, 2
	v_and_b32_e32 v179, 32, v132
	v_lshlrev_b32_e32 v7, 1, v132
	v_lshlrev_b32_e32 v178, 4, v5
	v_or_b32_e32 v5, v6, v179
	v_and_b32_e32 v7, 32, v7
	v_lshl_or_b32 v5, v5, 8, v7
	v_and_b32_e32 v7, 24, v4
	v_lshlrev_b32_e32 v4, 6, v6
	v_bfe_u32 v9, v132, 4, 2
	v_or3_b32 v187, v5, v4, v7
	v_or_b32_e32 v4, s22, v9
	s_movk_i32 s14, 0x80
	v_ashrrev_i32_e32 v5, 31, v4
	v_bitop3_b32 v193, v187, s14, v216 bitop3:0x36
	s_movk_i32 s14, 0xc0
	v_lshlrev_b64 v[134:135], 11, v[4:5]
	v_bitop3_b32 v4, s22, v132, v9 bitop3:0x36
	v_bitop3_b32 v194, v187, s14, v216 bitop3:0x36
	v_lshlrev_b32_e32 v4, 3, v4
	s_movk_i32 s14, 0x78
	v_sub_f32_e32 v172, 1.0, v2
	v_and_b32_e32 v2, 63, v132
	v_and_or_b32 v136, v4, s14, v134
	v_xor_b32_e32 v4, v6, v9
	v_and_b32_e32 v16, 15, v132
	v_lshlrev_b32_e32 v6, 5, v4
	v_bfe_u32 v4, v2, 4, 1
	v_cmp_eq_u32_e32 vcc, v16, v4
	v_or_b32_e32 v5, 16, v8
	v_cvt_f32_ubyte0_e32 v5, v5
	v_cndmask_b32_e32 v4, 0, v217, vcc
	v_pack_b32_f16 v116, v4, v4
	v_cvt_f32_ubyte0_e32 v4, v8
	v_cvt_f16_f32_e32 v4, v4
	v_cvt_f16_f32_e32 v5, v5
; __device__ __forceinline__ void da_phase(LAS unsigned char* lds, const GAS f16* __restrict__ kv, const GAS f16* __restrict__ qg, GAS f16* __restrict__ mixed, int vcu, int G, ...
;     ...
;     { const int q_ = (lane & 15) >> 2;
; #pragma unroll
;       for (int d0 = 0; d0 < 4; ++d0) vfo[d0] = DA_VRING + (32 * hi + q_) * 256 + ((d0 ^ q_) * 64) + ((lane >> 4) & 1) * 32 + (lane & 3) * 8; }
;     const int srow = 4 * w + (lane >> 4);
;     const size_t koff = (size_t)srow * KVW + K_DAK + (((lane & 15) ^ (srow & 15)) * 8);
;     const size_t voff = (size_t)srow * KVW + K_DAV + (((((lane & 15) >> 2) ^ (srow & 3)) * 4 + (lane & 3)) * 8);
;     const size_t qoff = S_DAQ * QG_SEC + bl512((size_t)(32 * rg + l31), c * 64 + 8 * hi);
;     h8 ones; { const f16 one = ((lane & 15) == ((lane >> 4) & 1)) ? (f16)1.0f : (f16)0.0f; ones = (h8){one, one, one, one, one, one, one, one}; }
;     h8 ba0, ba1; { const f16 z = (f16)0.0f, one = hi ? z : (f16)1.0f, k0 = hi ? z : (f16)(float)keyrow(l31), k1 = hi ? z : (f16)(float)(keyrow(l31) + 16);
;                    ba0 = (h8){one, one, k0, k0, z, z, z, z}; ba1 = (h8){one, one, k1, k1, z, z, z, z}; }
;     if (tid < 128) ((LAS float*)(lds + DA_SUBG))[tid] = subg[tid];
;     LAS unsigned* xch = (LAS unsigned*)(lds + DA_XCH + rg * 8192);
;     ...
;     DaUnit U, Un; int ui = vcu;
;     if (!da_decode(ui, U)) return;
;     const GAS f16* ksrc = kv + ((size_t)U.b * SEQ) * KVW + U.h * 128 + koff; const GAS f16* vsrc = kv + ((size_t)U.b * SEQ) * KVW + U.h * 128 + voff;
;     h8 qn[4];
;     { const GAS f16* Qg = qg + bl512((size_t)U.b * SEQ + U.qt * 128, U.h * 128) + qoff;
; #pragma unroll
;       for (int d0 = 0; d0 < 4; ++d0) qn[d0] = *(const GAS h8*)(Qg + 512 * d0); }
;     asm volatile("" : "+v"(qn[0]), "+v"(qn[1]), "+v"(qn[2]), "+v"(qn[3]));
;     DA_DMA(ksrc, vsrc, U.klo, 0, 0); DA_DMA(ksrc, vsrc, U.klo + 1, DA_KS, DA_KS);
;     int ik = 2 * DA_KS, iv = 2 * DA_KS, ck = 0, cv = 0;
;     for (;;) {
;         const size_t rowbase = (size_t)U.b * SEQ;
;         const int qw = U.qt * 128 + 32 * rg, t = qw + l31, lastt = qw >> 6, NT = 2 * U.qt + 2;
;         const int kfirst = U.klo + ((rg >> 1) & (U.klo > 0 ? 1 : 0));
;         const float cslope = exp2f(-2.0f * (float)(U.h + 1)) * LOG2E;
;         const float cs64 = 64.0f * cslope, base0 = -cslope * (float)(t - 32 * hi) - mref;
;         const float bt0 = -cslope * (float)t - mref;
	v_cmp_gt_u32_e64 s[40:41], 32, v2
	v_mov_b32_e32 v137, v135
	v_or3_b32 v134, v6, v7, v134
	v_cndmask_b32_e64 v4, 0, v4, s[40:41]
	v_cndmask_b32_e64 v5, 0, v5, s[40:41]
	s_ashr_i32 s21, s20, 31
	v_lshlrev_b32_e32 v174, 8, v8
	v_cndmask_b32_e64 v8, 0, v217, s[40:41]
	v_pack_b32_f16 v121, v4, v4
	v_pack_b32_f16 v125, v5, v5
	v_lshl_add_u64 v[4:5], v[136:137], 1, s[4:5]
	v_lshl_add_u64 v[6:7], v[134:135], 1, s[4:5]
	s_lshl_b64 s[4:5], s[20:21], 18
	v_pack_b32_f16 v120, v8, v8
	s_mov_b64 s[18:19], 0x800
	v_lshl_add_u64 v[8:9], v[4:5], 0, s[4:5]
	s_mov_b64 s[28:29], 0x20800
	v_lshl_add_u64 v[12:13], v[8:9], 0, s[18:19]
	s_mov_b32 s14, m0
	s_mov_b32 m0, s31
	s_nop 0
	global_load_lds_dwordx4 v[12:13], off
	s_mov_b32 m0, s14
	v_lshl_add_u64 v[8:9], v[8:9], 0, s[28:29]
	s_mov_b64 s[24:25], 0xc00
	s_add_i32 s14, s31, 0x2000
	s_mov_b32 s15, m0
	s_mov_b32 m0, s14
	s_nop 0
	global_load_lds_dwordx4 v[8:9], off
	s_mov_b32 m0, s15
	v_lshl_add_u64 v[8:9], v[6:7], 0, s[4:5]
	v_lshl_add_u64 v[12:13], v[8:9], 0, s[24:25]
	s_mov_b32 s14, m0
	s_mov_b32 m0, s34
	s_nop 0
	global_load_lds_dwordx4 v[12:13], off
	s_mov_b32 m0, s14
	s_add_i32 s14, s34, 0x2000
	s_add_u32 s4, s4, 0x40000
	s_mov_b64 s[42:43], 0x20c00
	s_addc_u32 s5, s5, 0
	v_lshl_add_u64 v[164:165], v[4:5], 0, s[18:19]
	v_lshl_add_u64 v[8:9], v[8:9], 0, s[42:43]
	s_mov_b32 s15, m0
	s_mov_b32 m0, s14
	s_nop 0
	global_load_lds_dwordx4 v[8:9], off
	s_mov_b32 m0, s15
	v_lshl_add_u64 v[4:5], v[4:5], 0, s[4:5]
	s_add_i32 s14, s31, 0x4000
	v_lshl_add_u64 v[8:9], v[4:5], 0, s[18:19]
	s_mov_b32 s18, m0
	s_mov_b32 m0, s14
	s_nop 0
	global_load_lds_dwordx4 v[8:9], off
	s_mov_b32 m0, s18
	v_lshl_add_u64 v[4:5], v[4:5], 0, s[28:29]
	s_add_i32 s14, s31, 0x6000
	s_mov_b32 s18, m0
	s_mov_b32 m0, s14
	s_nop 0
	global_load_lds_dwordx4 v[4:5], off
	s_mov_b32 m0, s18
	v_lshl_add_u64 v[4:5], v[6:7], 0, s[4:5]
	v_lshl_add_u64 v[166:167], v[6:7], 0, s[24:25]
	s_add_i32 s15, s31, 0x10000
	v_lshl_add_u64 v[6:7], v[4:5], 0, s[24:25]
	s_mov_b32 s4, m0
	s_mov_b32 m0, s15
	s_nop 0
	global_load_lds_dwordx4 v[6:7], off
	s_mov_b32 m0, s4
	s_add_i32 s4, s31, 0x12000
	s_bfe_u32 s21, s11, 0x10001
	s_cmpk_lt_u32 s0, 0x100
	v_lshl_add_u64 v[4:5], v[4:5], 0, s[42:43]
	s_mov_b32 s5, m0
	s_mov_b32 m0, s4
	s_nop 0
	global_load_lds_dwordx4 v[4:5], off
	s_mov_b32 m0, s5
	s_cselect_b64 s[44:45], -1, 0
	s_xor_b32 s4, s1, 1
	s_lshl_b32 s6, s6, 8
	v_lshlrev_b32_e32 v4, 2, v2
	s_lshl_b32 s5, s4, 12
	s_add_i32 s6, s6, 0
	v_and_b32_e32 v173, 31, v132
	v_add_u32_e32 v5, s7, v4
	s_add_i32 s7, s7, s5
	s_lshl_b32 s5, s1, 12
	s_add_i32 s6, s6, 0x24c00
	s_lshl_b32 s1, s1, 7
	v_add_u32_e32 v196, s7, v4
	s_add_i32 s1, s6, s1
	v_lshlrev_b32_e32 v4, 2, v173
	v_add_u32_e32 v197, s1, v4
	s_lshl_b32 s1, s4, 7
	s_and_b32 s0, s0, 0xffffff00
	s_add_i32 s6, s6, s1
	s_add_i32 s0, s0, 0
	v_add_u32_e32 v198, s6, v4
	s_add_i32 s0, s0, 0x24400
	v_lshlrev_b32_e32 v4, 4, v14
	v_lshlrev_b32_e32 v2, 8, v14
	v_and_or_b32 v6, v213, 64, v16
	v_xor_b32_e32 v140, 0x80000000, v133
	v_cndmask_b32_e64 v156, -1.0, 1.0, s[44:45]
	v_add_u32_e32 v201, s0, v4
	v_readlane_b32 s0, v251, 14
	v_bitop3_b32 v192, v187, 64, v216 bitop3:0x36
	v_mov_b32_e32 v117, v116
	v_mov_b32_e32 v118, v116
	v_mov_b32_e32 v119, v116
	v_mov_b32_e32 v122, v3
	v_mov_b32_e32 v123, v3
	v_mov_b32_e32 v124, v120
	v_mov_b32_e32 v126, v3
	v_mov_b32_e32 v127, v3
	s_mov_b64 s[60:61], 0x800
	s_mov_b64 s[62:63], 0xc00
	v_lshl_add_u64 v[138:139], s[82:83], 0, v[10:11]
	v_cmp_gt_u32_e64 s[42:43], 16, v173
	v_cndmask_b32_e64 v195, v15, 1.0, s[44:45]
	v_lshlrev_b32_e32 v199, 2, v6
	v_mov_b32_e32 v141, v140
	v_mov_b32_e32 v142, v140
	v_mov_b32_e32 v143, v140
	v_mov_b32_e32 v144, v140
	v_mov_b32_e32 v145, v140
	v_mov_b32_e32 v146, v140
	v_mov_b32_e32 v147, v140
	v_mov_b32_e32 v148, v140
	v_mov_b32_e32 v149, v140
	v_mov_b32_e32 v150, v140
	v_mov_b32_e32 v151, v140
	v_mov_b32_e32 v152, v140
	v_mov_b32_e32 v153, v140
	v_mov_b32_e32 v154, v140
	v_mov_b32_e32 v155, v140
	v_mov_b32_e32 v157, v156
	s_mov_b32 s57, 0x8000
	s_mov_b32 s37, 0
	v_lshlrev_b32_e32 v158, 1, v2
	v_add_u32_e32 v200, s5, v5
	s_mov_b32 s6, s0
	s_mov_b32 s0, s23
	s_mov_b32 s55, 0
	s_mov_b32 s22, 0x8000
	s_mov_b32 s56, s79
	s_branch .LBB0_491

; #define SW_END(id) do { if (SW_ID == (id)) sw_acc += __builtin_amdgcn_s_memrealtime() - sw_t0_##id; } while (0)
; #define SW_END(id) do {} while (0)
; #define GAS __attribute__((address_space(1)))
; __host__ __device__ __forceinline__ size_t bl512(size_t row, int col) { return ((row >> 5) * 64 + (size_t)(col >> 3)) * 256 + (row & 31) * 8 + (col & 7); }
; __device__ __forceinline__ void da_phase(LAS unsigned char* lds, const GAS f16* __restrict__ kv, const GAS f16* __restrict__ qg, GAS f16* __restrict__ mixed, int vcu, int G, ...
;     ...
;         asm volatile("s_nop 15\n\ts_nop 7" : "+v"(o[0]), "+v"(o[1]), "+v"(o[2]), "+v"(o[3]), "+v"(osum));
;         SW_END(2);
;         const int dlo = 2 * c;
;         u32x4 gr[4];
;         ld_groups_raw_bl(qg + S_DAG * QG_SEC + bl512(grow, U.h * 128 + 32 * dlo), hi, gr);
;         if (has_next) { const GAS f16* Qg = qg + bl512((size_t)Un.b * SEQ + Un.qt * 128, Un.h * 128) + qoff;
; #pragma unroll
;             for (int d0 = 0; d0 < 4; ++d0) qn[d0] = *(const GAS h8*)(Qg + 512 * d0); }
.LBB0_526:
	s_ashr_i32 s7, s6, 31
	s_lshl_b64 s[6:7], s[6:7], 11
	s_ashr_i32 s10, s1, 31
	s_add_u32 s6, s6, s1
	s_addc_u32 s7, s7, s10
	s_lshl_b32 s0, s0, 7
	s_add_i32 s0, s0, s36
	s_lshl_b64 s[10:11], s[6:7], 1
	s_and_b32 s1, s11, 0x7fffff
	s_ashr_i32 s11, s0, 3
	s_andn2_b32 s10, s10, 63
	s_ashr_i32 s14, s11, 31
	s_add_u32 s10, s10, s11
	v_or_b32_e32 v2, s6, v132
	s_addc_u32 s11, s1, s14
	v_lshlrev_b32_e32 v2, 3, v2
	s_lshl_b64 s[10:11], s[10:11], 9
	v_and_b32_e32 v2, 0xf8, v2
	s_add_u32 s10, s27, s10
	s_addc_u32 s11, s30, s11
	v_lshlrev_b32_e32 v2, 1, v2
	v_lshl_add_u64 v[68:69], s[10:11], 0, v[2:3]
	v_mov_b32_e32 v159, v3
	v_lshl_add_u64 v[68:69], v[68:69], 0, v[158:159]
	s_nop 15
	s_nop 7
	global_load_dwordx4 v[80:83], v[68:69], off nt
	global_load_dwordx4 v[76:79], v[68:69], off offset:1024 nt
	global_load_dwordx4 v[72:75], v[68:69], off offset:2048 nt
	s_nop 0
	global_load_dwordx4 v[68:71], v[68:69], off offset:3072 nt
	s_and_b64 vcc, exec, s[4:5]
	s_cbranch_vccz .LBB0_528
	s_lshl_b32 s4, s28, 7
	s_ashr_i32 s53, s52, 31
	s_ashr_i32 s5, s4, 31
	s_lshl_b64 s[10:11], s[52:53], 12
	s_lshl_b64 s[4:5], s[4:5], 1
	s_add_u32 s1, s10, s4
	s_addc_u32 s5, s11, s5
	s_lshl_b32 s4, s54, 4
	s_ashr_i32 s10, s4, 31
	s_add_u32 s4, s1, s4
	s_addc_u32 s5, s5, s10
	s_lshl_b64 s[4:5], s[4:5], 9
	v_lshl_add_u64 v[84:85], v[138:139], 0, s[4:5]
	global_load_dwordx4 v[100:103], v[84:85], off nt
	global_load_dwordx4 v[104:107], v[84:85], off offset:1024 nt
	global_load_dwordx4 v[108:111], v[84:85], off offset:2048 nt
	global_load_dwordx4 v[112:115], v[84:85], off offset:3072 nt

; #define LAS __attribute__((address_space(3)))
; #define GAS __attribute__((address_space(1)))
; __host__ __device__ __forceinline__ size_t bl512(size_t row, int col) { return ((row >> 5) * 64 + (size_t)(col >> 3)) * 256 + (row & 31) * 8 + (col & 7); }
; __device__ __forceinline__ void sb_phase(LAS unsigned char* lds, const GAS f16* __restrict__ kv, const GAS f16* __restrict__ qg, GAS f16* __restrict__ mixed, int vcu, int G, unsigned long long& sw_acc) {
;     int tid_ = threadIdx.x; asm volatile("" : "+v"(tid_));
;     const int tid = tid_, lane = tid & 63, l31 = lane & 31, hi = lane >> 5; const int w = __builtin_amdgcn_readfirstlane(tid >> 6);
;     const int rgp = w >> 2, hh = (w + 2 * rgp) & 3;
;     const unsigned lds0 = (unsigned)(uintptr_t)lds;
;     const unsigned kdst = lds0 + w * 4096, vdst = lds0 + 32768 + w * 4096;
;     int kfo[4];
;     { const int kr = keyrow16(l31);
; #pragma unroll
;       for (int d0 = 0; d0 < 4; ++d0) kfo[d0] = kr * 512 + (((hh * 8 + 2 * d0 + hi) ^ (kr & 15)) * 16); }
;     int vfo[2];
;     { const int q_ = (lane & 15) >> 2;
; #pragma unroll
;       for (int d0 = 0; d0 < 2; ++d0) vfo[d0] = 32768 + (16 * hi + q_) * 512 + (((hh * 2 + d0) ^ q_) * 64) + ((lane >> 4) & 1) * 32 + (lane & 3) * 8; }
;     LAS unsigned* flags = (LAS unsigned*)(lds + SB_FLG);
;     size_t koff[4], voff[4];
; #pragma unroll
;     for (int i = 0; i < 4; ++i) { const int row = 8 * w + 2 * i + (lane >> 5), p = lane & 31;
;         koff[i] = (size_t)row * KVW + K_SBK + ((p ^ (row & 15)) * 8);
;         voff[i] = (size_t)row * KVW + K_SBV + ((((p >> 2) ^ (row & 3)) * 4 + (p & 3)) * 8); }
;     ...
;     SbUnit U, Un; int ui = vcu;
;     if (!sb_decode(ui, U)) return;
;     if (w >= 4) __builtin_amdgcn_s_setprio(1);
;     int islot = 0, cslot = 0;
;     const GAS f16* tbase = kv + ((size_t)U.b * SEQ) * KVW + U.hg * 256;
;     h8 qn[4]; u32x4 gn[4];
;     { const size_t grow = (size_t)U.b * SEQ + U.cq * 64 + 32 * rgp + l31; const int h = 4 * U.hg + hh;
;       const GAS f16* Qg = qg + S_SBQ * QG_SEC + bl512(grow, h * 64 + 8 * hi); const GAS f16* Gp = qg + S_SBG * QG_SEC + bl512(grow, h * 64);
; #pragma unroll
;       for (int d0 = 0; d0 < 4; ++d0) qn[d0] = *(const GAS h8*)(Qg + 512 * d0);
;       ld_groups_raw_bl(Gp, hi, gn); }
;     asm volatile("" : "+v"(qn[0]), "+v"(qn[1]), "+v"(qn[2]), "+v"(qn[3]));
;     SB_DMA(tbase, U.cq, islot); islot ^= SB_SLOT;
.LBB0_534:
	v_readlane_b32 s6, v250, 0
	v_readlane_b32 s7, v250, 1
	s_add_u32 s27, s6, 0x14000000
	s_addc_u32 s22, s7, 0
	s_ashr_i32 s6, s1, 8
	s_lshl_b32 s0, s6, 1
	s_add_i32 s0, s0, s4
	s_lshl_b32 s5, s4, 12
	s_and_b32 s0, s0, 3
	s_add_i32 s23, s5, 0
	s_lshl_b32 s11, s6, 5
	s_lshl_b32 s5, s0, 3
	s_lshl_b32 s7, s0, 1
	s_add_i32 s10, s23, 0x8000
	s_ashr_i32 s14, s11, 31
	v_readlane_b32 s15, v251, 15
	s_add_u32 s18, s15, s11
	v_readlane_b32 s15, v251, 16
	v_lshlrev_b32_e32 v2, 2, v4
	v_lshrrev_b32_e32 v5, 1, v4
	s_addc_u32 s19, s15, s14
	s_lshl_b32 s15, s0, 6
	v_readlane_b32 s20, v251, 13
	v_and_b32_e32 v2, 16, v2
	v_and_b32_e32 v12, 3, v4
	v_and_b32_e32 v5, 12, v5
	s_or_b32 s0, s20, s15
	v_bfe_u32 v11, v4, 5, 1
	v_or3_b32 v8, v12, v2, v5
	v_or_b32_e32 v2, s18, v4
	s_lshl_b64 s[18:19], s[18:19], 1
	s_lshr_b32 s0, s0, 3
	s_and_b32 s19, s19, 0xffffff
	s_andn2_b32 s18, s18, 63
	v_or_b32_e32 v6, s0, v11
	v_or_b32_e32 v6, s18, v6
	v_mov_b32_e32 v7, s19
	v_lshlrev_b64 v[6:7], 9, v[6:7]
	v_lshlrev_b32_e32 v2, 4, v2
	v_lshl_add_u64 v[6:7], s[82:83], 0, v[6:7]
	v_and_b32_e32 v2, 0x1f0, v2
	v_lshl_add_u64 v[6:7], v[6:7], 0, v[2:3]
	global_load_dwordx4 v[64:67], v[6:7], off offset:3072 nt
	global_load_dwordx4 v[60:63], v[6:7], off offset:2048 nt
	global_load_dwordx4 v[56:59], v[6:7], off offset:1024 nt
	global_load_dwordx4 v[52:55], v[6:7], off nt
	v_or_b32_e32 v5, v5, v12
	v_lshlrev_b32_e32 v6, 9, v8
	v_or_b32_e32 v7, s5, v11
	v_bitop3_b32 v8, s5, v5, v11 bitop3:0x36
	v_lshl_or_b32 v117, v8, 4, v6
	v_bitop3_b32 v8, v7, v5, 2 bitop3:0x36
	v_lshl_or_b32 v135, v8, 4, v6
	v_bitop3_b32 v8, v7, v5, 4 bitop3:0x36
	v_bitop3_b32 v5, v7, v5, 6 bitop3:0x36
	s_or_b32 s18, s18, s0
	v_lshl_or_b32 v152, v8, 4, v6
	v_lshl_or_b32 v153, v5, 4, v6
	v_bfe_u32 v6, v4, 2, 2
	s_lshl_b64 s[18:19], s[18:19], 9
	v_lshlrev_b32_e32 v7, 9, v6
	v_lshlrev_b32_e32 v8, 1, v4
	v_lshlrev_b32_e32 v9, 3, v4
	s_add_u32 s18, s27, s18
	v_lshl_or_b32 v7, v11, 13, v7
	v_and_b32_e32 v8, 32, v8
	v_and_b32_e32 v9, 24, v9
	s_addc_u32 s19, s22, s19
	v_or3_b32 v13, v7, v8, v9
	v_lshl_add_u64 v[8:9], s[18:19], 0, v[2:3]
	v_lshlrev_b32_e32 v2, 9, v11
	v_lshl_add_u64 v[8:9], v[8:9], 0, v[2:3]
	global_load_dwordx4 v[68:71], v[8:9], off nt
	global_load_dwordx4 v[72:75], v[8:9], off offset:1024 nt
	global_load_dwordx4 v[76:79], v[8:9], off offset:2048 nt
	global_load_dwordx4 v[80:83], v[8:9], off offset:3072 nt
	v_bitop3_b32 v15, s7, v6, 1 bitop3:0x36
	v_lshl_or_b32 v6, s4, 3, v11
	v_and_b32_e32 v116, 31, v4
	v_lshrrev_b32_e32 v5, 2, v4
	v_ashrrev_i32_e32 v7, 31, v6
	v_bitop3_b32 v14, s7, v5, 3 bitop3:0x78
	v_lshlrev_b64 v[118:119], 11, v[6:7]
	v_bitop3_b32 v5, v6, v116, 9 bitop3:0x6c
	v_lshl_or_b32 v120, v5, 3, v118
	v_lshlrev_b32_e32 v5, 2, v11
	v_and_b32_e32 v10, 63, v4
	v_and_b32_e32 v16, 28, v4
	v_bitop3_b32 v4, v5, v4, 28 bitop3:0x78
	v_or_b32_e32 v4, v4, v12
	v_lshlrev_b32_e32 v7, 3, v4
	v_or_b32_e32 v4, 2, v6
	v_readlane_b32 s0, v251, 8
	v_ashrrev_i32_e32 v5, 31, v4
	v_lshlrev_b32_e32 v2, 2, v4
	s_add_u32 s0, s8, s0
	v_lshlrev_b64 v[122:123], 11, v[4:5]
	v_bitop3_b32 v5, v4, v116, 11 bitop3:0x6c
	v_bitop3_b32 v2, v2, v16, 12 bitop3:0x6c
	v_or_b32_e32 v4, 4, v6
	s_addc_u32 s5, s9, 0
	s_lshl_b32 s7, s20, 1
	v_lshl_or_b32 v124, v5, 3, v122
	v_or_b32_e32 v2, v2, v12
	v_ashrrev_i32_e32 v5, 31, v4
	s_add_u32 s49, s0, s7
	v_lshl_or_b32 v122, v2, 3, v122
	v_lshlrev_b64 v[126:127], 11, v[4:5]
	v_bitop3_b32 v2, v4, v116, 13 bitop3:0x6c
	v_or_b32_e32 v4, 6, v6
	s_addc_u32 s0, s5, 0
	v_readlane_b32 s18, v251, 19
	v_ashrrev_i32_e32 v5, 31, v4
	v_readlane_b32 s19, v251, 20
	s_add_u32 s18, s49, s18
	v_mov_b32_e32 v121, v119
	v_lshl_or_b32 v128, v2, 3, v126
	v_lshlrev_b64 v[130:131], 11, v[4:5]
	v_bitop3_b32 v2, v4, v116, 15 bitop3:0x6c
	s_addc_u32 s19, s0, s19
	v_or_b32_e32 v118, v118, v7
	v_lshl_or_b32 v132, v2, 3, v130
	v_lshlrev_b32_e32 v2, 2, v4
	v_lshl_add_u64 v[4:5], v[120:121], 1, s[18:19]
	s_mov_b32 s5, m0
	s_mov_b32 m0, s23
	s_nop 0
	global_load_lds_dwordx4 v[4:5], off
	s_mov_b32 m0, s5
	v_lshl_add_u64 v[4:5], v[118:119], 1, s[18:19]
	v_mov_b32_e32 v125, v123
	v_lshl_add_u64 v[4:5], v[4:5], 0, s[2:3]
	s_mov_b32 s5, m0
	s_mov_b32 m0, s10
	s_nop 0
	global_load_lds_dwordx4 v[4:5], off
	s_mov_b32 m0, s5
	v_lshl_add_u64 v[4:5], v[124:125], 1, s[18:19]
	s_add_i32 s5, s23, 0x400
	s_mov_b32 s7, m0
	s_mov_b32 m0, s5
	s_nop 0
	global_load_lds_dwordx4 v[4:5], off
	s_mov_b32 m0, s7
	v_lshl_add_u64 v[4:5], v[122:123], 1, s[18:19]
	v_mov_b32_e32 v129, v127
	v_lshl_add_u64 v[4:5], v[4:5], 0, s[2:3]
	s_add_i32 s5, s10, 0x400
	v_or_b32_e32 v126, v126, v7
	s_mov_b32 s7, m0
	s_mov_b32 m0, s5
	s_nop 0
	global_load_lds_dwordx4 v[4:5], off
	s_mov_b32 m0, s7
	v_lshl_add_u64 v[4:5], v[128:129], 1, s[18:19]
	s_add_i32 s5, s23, 0x800
	v_bitop3_b32 v2, v2, v16, 12 bitop3:0x6c
	s_mov_b32 s7, m0
	s_mov_b32 m0, s5
	s_nop 0
	global_load_lds_dwordx4 v[4:5], off
	s_mov_b32 m0, s7
	v_lshl_add_u64 v[4:5], v[126:127], 1, s[18:19]
	s_add_i32 s5, s10, 0x800
	s_lshl_b32 s4, s4, 2
	v_mov_b32_e32 v133, v131
	v_or_b32_e32 v2, v2, v12
	v_lshl_add_u64 v[4:5], v[4:5], 0, s[2:3]
	s_mov_b32 s7, m0
	s_mov_b32 m0, s5
	s_nop 0
	global_load_lds_dwordx4 v[4:5], off
	s_mov_b32 m0, s7
	s_add_i32 s5, s23, 0xc00
	s_add_i32 s48, s4, 0
	v_lshl_or_b32 v130, v2, 3, v130
	v_lshl_add_u64 v[4:5], v[132:133], 1, s[18:19]
	s_mov_b32 s7, m0
	s_mov_b32 m0, s5
	s_nop 0
	global_load_lds_dwordx4 v[4:5], off
	s_mov_b32 m0, s7
	s_add_i32 s5, s10, 0xc00
	s_add_i32 s48, s48, 0x24800
	v_lshl_add_u64 v[4:5], v[130:131], 1, s[18:19]
	s_cmp_eq_u32 s6, 1
	v_lshl_add_u64 v[4:5], v[4:5], 0, s[2:3]
	s_mov_b32 s7, m0
	s_mov_b32 m0, s5
	s_nop 0
	global_load_lds_dwordx4 v[4:5], off
	s_mov_b32 m0, s7
	s_cselect_b64 s[4:5], -1, 0
	s_cmp_lg_u32 s6, 1
	v_readlane_b32 s18, v251, 17
	s_cselect_b64 s[6:7], -1, 0
	s_cmpk_gt_u32 s1, 0xff
	s_mov_b32 s29, s18
	v_readlane_b32 s18, v251, 14
	v_lshlrev_b32_e32 v154, 3, v11
	v_lshlrev_b32_e32 v134, 8, v11
	s_cselect_b64 s[20:21], -1, 0
	v_lshlrev_b32_e32 v155, 4, v11
	v_cmp_gt_u32_e64 s[38:39], 32, v10
	s_mov_b32 s76, 0
	v_cmp_eq_u32_e64 s[40:41], 0, v10
	v_lshl_or_b32 v156, v14, 6, v13
	v_lshl_or_b32 v157, v15, 6, v13
	s_mov_b32 s50, 0x10000
	v_readlane_b32 s1, v251, 12
	s_mov_b32 s28, s18
	v_readlane_b32 s19, v251, 18
	s_waitcnt vmcnt(0)
	s_branch .LBB0_537

; #define SW_BEGIN(id) unsigned long long sw_t0_##id = 0; if (SW_ID == (id)) sw_t0_##id = __builtin_amdgcn_s_memrealtime()
; #define SW_BEGIN(id) do {} while (0)
; #define GAS __attribute__((address_space(1)))
; __host__ __device__ __forceinline__ size_t bl512(size_t row, int col) { return ((row >> 5) * 64 + (size_t)(col >> 3)) * 256 + (row & 31) * 8 + (col & 7); }
; #define WAIT_BAR(N) asm volatile("s_waitcnt vmcnt(" #N ") lgkmcnt(0)\n\ts_barrier" ::: "memory")
; __device__ __forceinline__ void sb_phase(LAS unsigned char* lds, const GAS f16* __restrict__ kv, const GAS f16* __restrict__ qg, GAS f16* __restrict__ mixed, int vcu, int G, unsigned long long& sw_acc) {
;     ...
;         const bool has_next = sb_decode(ui + G, Un);
;         f32x16 o[2]; o[0] = f32x16{}; o[1] = f32x16{};
;         float carry = 1.f; int done = 0;
;         bool spec = false, late = false; int nslot = 0;
;         const GAS f16* tbn = has_next ? kv + ((size_t)Un.b * SEQ) * KVW + Un.hg * 256 : tbase;
;         SW_BEGIN(12);
;         for (int j = 0; j < NT; ++j) {
;             SW_BEGIN(13);
;             WAIT_BAR(0);
;     ...
;         if (has_next) {
;             const size_t grown = (size_t)Un.b * SEQ + Un.cq * 64 + 32 * rgp + l31; const int hn = 4 * Un.hg + hh;
;             const GAS f16* Qg = qg + S_SBQ * QG_SEC + bl512(grown, hn * 64 + 8 * hi); const GAS f16* Gp = qg + S_SBG * QG_SEC + bl512(grown, hn * 64);
; #pragma unroll
;             for (int d0 = 0; d0 < 4; ++d0) qn[d0] = *(const GAS h8*)(Qg + 512 * d0);
;             ld_groups_raw_bl(Gp, hi, gn);
.LBB0_539:
	s_lshl_b32 s51, s29, 6
	s_add_i32 s85, s51, s11
	s_cmp_lt_i32 s29, 0
	s_mov_b32 s53, 0
	s_cbranch_scc1 .LBB0_553
	s_ashr_i32 s31, s30, 31
	s_lshl_b64 s[36:37], s[30:31], 23
	s_add_u32 s19, s8, s36
	s_addc_u32 s31, s9, s37
	s_lshl_b32 s36, s84, 8
	s_ashr_i32 s37, s36, 31
	s_lshl_b64 s[36:37], s[36:37], 1
	s_add_u32 s19, s19, s36
	s_addc_u32 s31, s31, s37
	s_and_b64 s[36:37], s[34:35], exec
	s_cselect_b32 s31, s31, s0
	s_cselect_b32 s42, s19, s49
	s_ashr_i32 s19, s18, 31
	s_lshl_b64 s[36:37], s[18:19], 18
	s_add_u32 s44, s42, s36
	s_addc_u32 s45, s31, s37
	s_cmp_lg_u32 s29, 0
	s_cselect_b64 s[42:43], -1, 0
	s_cmp_eq_u32 s29, 0
	s_waitcnt vmcnt(4) lgkmcnt(0)
	s_barrier
	s_cselect_b64 s[36:37], -1, 0
	s_andn2_b64 vcc, exec, s[34:35]
	s_cbranch_vccnz .Lsb_pf_skip
	s_ashr_i32 s47, s30, 31
	s_mov_b32 s46, s30
	s_lshl_b64 s[46:47], s[46:47], 11
	s_lshl_b32 s19, s18, 6
	s_ashr_i32 s31, s19, 31
	s_add_u32 s19, s19, s11
	s_addc_u32 s31, s31, s14
	s_add_u32 s46, s19, s46
	s_addc_u32 s47, s31, s47
	s_lshl_b32 s19, s84, 8
	s_or_b32 s19, s19, s15
	v_or_b32_e32 v236, s19, v154
	v_or_b32_e32 v238, s46, v116
	s_lshl_b64 s[46:47], s[46:47], 1
	v_ashrrev_i32_e32 v234, 3, v236
	s_ashr_i32 s19, s19, 3
	s_and_b32 s47, s47, 0xffffff
	s_andn2_b32 s46, s46, 63
	v_ashrrev_i32_e32 v235, 31, v234
	s_ashr_i32 s31, s19, 31
	v_lshl_add_u64 v[234:235], s[46:47], 0, v[234:235]
	s_add_u32 s46, s46, s19
	s_addc_u32 s47, s47, s31
	v_lshlrev_b64 v[234:235], 9, v[234:235]
	v_lshlrev_b32_e32 v238, 4, v238
	s_lshl_b64 s[46:47], s[46:47], 9
	v_lshl_add_u64 v[234:235], s[82:83], 0, v[234:235]
	v_and_b32_e32 v238, 0x1f0, v238
	v_mov_b32_e32 v239, 0
	s_add_u32 s46, s27, s46
	v_lshl_add_u64 v[234:235], v[234:235], 0, v[238:239]
	s_addc_u32 s47, s22, s47
	global_load_dwordx4 v[218:221], v[234:235], off nt
	global_load_dwordx4 v[222:225], v[234:235], off offset:1024 nt
	global_load_dwordx4 v[226:229], v[234:235], off offset:2048 nt
	global_load_dwordx4 v[230:233], v[234:235], off offset:3072 nt
	v_lshl_add_u64 v[236:237], s[46:47], 0, v[238:239]
	v_lshlrev_b32_e32 v240, 1, v134
	v_mov_b32_e32 v241, 0
	v_lshl_add_u64 v[236:237], v[236:237], 0, v[240:241]
	global_load_dwordx4 v[68:71], v[236:237], off nt
	global_load_dwordx4 v[72:75], v[236:237], off offset:1024 nt
	global_load_dwordx4 v[76:79], v[236:237], off offset:2048 nt
	global_load_dwordx4 v[80:83], v[236:237], off offset:3072 nt
